# adds: P3 tail_gemm items re-tiled to 64x64 sub-tiles (both passes)
# speedup vs baseline: 1.0481x; 1.0087x over previous
.LBB0_1014:
	s_mov_b32 s40, 0x4000
	s_mov_b32 s41, 0
	s_mov_b32 s42, 0x8000
	s_mov_b32 s43, 0
	s_mov_b32 s44, 0xc000
	s_mov_b32 s45, 0
	s_ashr_i32 s26, s25, 4
	s_add_i32 s26, s26, s33
	s_ashr_i32 s27, s26, 31
	s_lshr_b32 s27, s27, 29
	s_add_i32 s27, s26, s27
	s_ashr_i32 s28, s27, 3
	s_and_b32 s27, s27, -8
	s_sub_i32 s26, s26, s27
	s_cmp_lt_i32 s26, 0
	s_cselect_b32 s27, 35, 34
	s_mul_i32 s26, s26, s27
	s_add_i32 s26, s26, s28
	s_ashr_i32 s27, s26, 31
	s_lshr_b32 s27, s27, 27
	s_add_i32 s27, s26, s27
	s_ashr_i32 s28, s27, 5
	s_andn2_b32 s27, s27, 31
	s_lshl_b32 s28, s28, 3
	s_sub_i32 s27, s26, s27
	s_sub_i32 s26, 0x44, s28
	s_min_i32 s26, s26, 8
	s_abs_i32 s31, s26
	v_cvt_f32_u32_e32 v4, s31
	s_sub_i32 s34, 0, s31
	s_abs_i32 s29, s27
	s_xor_b32 s30, s27, s26
	v_rcp_iflag_f32_e32 v4, v4
	s_ashr_i32 s30, s30, 31
	v_mul_f32_e32 v4, 0x4f7ffffe, v4
	v_cvt_u32_f32_e32 v4, v4
	s_nop 0
	v_readfirstlane_b32 s35, v4
	s_mul_i32 s34, s34, s35
	s_mul_hi_u32 s34, s35, s34
	s_add_i32 s35, s35, s34
	s_mul_hi_u32 s34, s29, s35
	s_mul_i32 s35, s34, s31
	s_sub_i32 s29, s29, s35
	s_add_i32 s37, s34, 1
	s_sub_i32 s35, s29, s31
	s_cmp_ge_u32 s29, s31
	s_cselect_b32 s34, s37, s34
	s_cselect_b32 s29, s35, s29
	s_add_i32 s35, s34, 1
	s_cmp_ge_u32 s29, s31
	s_cselect_b32 s29, s35, s34
	s_xor_b32 s29, s29, s30
	s_sub_i32 s29, s29, s30
	s_mul_i32 s30, s29, s26
	s_waitcnt vmcnt(0) lgkmcnt(0)
	s_lshl_b32 s26, s29, 8
	s_and_b32 s32, s10, 0x30
	s_lshl_b32 s32, s32, 2
	s_or_b32 s26, s26, s32
	v_or_b32_e32 v4, s26, v179
	v_ashrrev_i32_e32 v5, 31, v4
	v_lshlrev_b64 v[4:5], 10, v[4:5]
	v_lshl_add_u64 v[194:195], v[2:3], 0, v[4:5]
	s_sub_i32 s27, s27, s30
	s_add_i32 s28, s28, s27
	s_and_b32 s31, s10, 0xc0
	s_lshl_b32 s27, s28, 8
	s_or_b32 s27, s27, s31
	v_or_b32_e32 v72, s27, v179
	v_ashrrev_i32_e32 v73, 31, v72
	v_lshlrev_b64 v[72:73], 10, v[72:73]
	v_lshl_add_u64 v[174:175], v[0:1], 0, v[72:73]
	s_add_i32 s25, s25, s94
	s_add_i32 s10, s10, s72
	s_cmp_lt_i32 s25, s36
	v_lshl_add_u64 v[188:189], v[174:175], 0, s[40:41]
	v_lshl_add_u64 v[196:197], v[194:195], 0, s[40:41]
	v_lshl_add_u64 v[190:191], v[174:175], 0, s[42:43]
	v_lshl_add_u64 v[198:199], v[194:195], 0, s[42:43]
	v_lshl_add_u64 v[192:193], v[174:175], 0, s[44:45]
	v_lshl_add_u64 v[200:201], v[194:195], 0, s[44:45]
	global_load_dwordx4 v[114:117], v[174:175], off
	global_load_dwordx4 v[118:121], v[174:175], off offset:64
	global_load_dwordx4 v[122:125], v[188:189], off
	global_load_dwordx4 v[126:129], v[188:189], off offset:64
	global_load_dwordx4 v[130:133], v[190:191], off
	global_load_dwordx4 v[134:137], v[190:191], off offset:64
	global_load_dwordx4 v[138:141], v[192:193], off
	global_load_dwordx4 v[142:145], v[192:193], off offset:64
	global_load_dwordx4 v[146:149], v[194:195], off
	global_load_dwordx4 v[150:153], v[194:195], off offset:64
	global_load_dwordx4 v[154:157], v[196:197], off
	global_load_dwordx4 v[158:161], v[196:197], off offset:64
	global_load_dwordx4 v[162:165], v[198:199], off
	global_load_dwordx4 v[166:169], v[198:199], off offset:64
	global_load_dwordx4 v[170:173], v[200:201], off
	global_load_dwordx4 v[184:187], v[200:201], off offset:64
	s_waitcnt vmcnt(0)
	v_mfma_f32_16x16x32_bf16 v[40:43], v[114:117], v[146:149], 0
	v_mfma_f32_16x16x32_bf16 v[46:49], v[114:117], v[154:157], 0
	v_mfma_f32_16x16x32_bf16 v[50:53], v[114:117], v[162:165], 0
	v_mfma_f32_16x16x32_bf16 v[54:57], v[114:117], v[170:173], 0
	v_mfma_f32_16x16x32_bf16 v[58:61], v[122:125], v[146:149], 0
	v_mfma_f32_16x16x32_bf16 v[64:67], v[122:125], v[154:157], 0
	v_mfma_f32_16x16x32_bf16 v[68:71], v[122:125], v[162:165], 0
	v_mfma_f32_16x16x32_bf16 v[78:81], v[122:125], v[170:173], 0
	v_mfma_f32_16x16x32_bf16 v[82:85], v[130:133], v[146:149], 0
	v_mfma_f32_16x16x32_bf16 v[86:89], v[130:133], v[154:157], 0
	v_mfma_f32_16x16x32_bf16 v[90:93], v[130:133], v[162:165], 0
	v_mfma_f32_16x16x32_bf16 v[94:97], v[130:133], v[170:173], 0
	v_mfma_f32_16x16x32_bf16 v[98:101], v[138:141], v[146:149], 0
	v_mfma_f32_16x16x32_bf16 v[102:105], v[138:141], v[154:157], 0
	v_mfma_f32_16x16x32_bf16 v[106:109], v[138:141], v[162:165], 0
	v_mfma_f32_16x16x32_bf16 v[110:113], v[138:141], v[170:173], 0
	v_mfma_f32_16x16x32_bf16 v[40:43], v[118:121], v[150:153], v[40:43]
	v_mfma_f32_16x16x32_bf16 v[46:49], v[118:121], v[158:161], v[46:49]
	v_mfma_f32_16x16x32_bf16 v[50:53], v[118:121], v[166:169], v[50:53]
	v_mfma_f32_16x16x32_bf16 v[54:57], v[118:121], v[184:187], v[54:57]
	v_mfma_f32_16x16x32_bf16 v[58:61], v[126:129], v[150:153], v[58:61]
	v_mfma_f32_16x16x32_bf16 v[64:67], v[126:129], v[158:161], v[64:67]
	v_mfma_f32_16x16x32_bf16 v[68:71], v[126:129], v[166:169], v[68:71]
	v_mfma_f32_16x16x32_bf16 v[78:81], v[126:129], v[184:187], v[78:81]
	v_mfma_f32_16x16x32_bf16 v[82:85], v[134:137], v[150:153], v[82:85]
	v_mfma_f32_16x16x32_bf16 v[86:89], v[134:137], v[158:161], v[86:89]
	v_mfma_f32_16x16x32_bf16 v[90:93], v[134:137], v[166:169], v[90:93]
	v_mfma_f32_16x16x32_bf16 v[94:97], v[134:137], v[184:187], v[94:97]
	v_mfma_f32_16x16x32_bf16 v[98:101], v[142:145], v[150:153], v[98:101]
	v_mfma_f32_16x16x32_bf16 v[102:105], v[142:145], v[158:161], v[102:105]
	v_mfma_f32_16x16x32_bf16 v[106:109], v[142:145], v[166:169], v[106:109]
	v_mfma_f32_16x16x32_bf16 v[110:113], v[142:145], v[184:187], v[110:113]
	s_barrier
	v_lshrrev_b32_e32 v45, 2, v211
	v_and_b32_e32 v45, 0x30, v45
	v_or3_b32 v72, v45, v210, s27
	v_ashrrev_i32_e32 v73, 31, v72
	v_and_b32_e32 v45, 0x2f, v211
	v_add_u32_e32 v4, s26, v45
	v_ashrrev_i32_e32 v5, 31, v4
	v_lshlrev_b64 v[4:5], 1, v[4:5]
	v_lshlrev_b64 v[62:63], 12, v[72:73]
	v_lshl_add_u64 v[74:75], s[60:61], 0, v[62:63]
	v_lshl_add_u64 v[74:75], v[74:75], 0, v[4:5]
	ds_write_b128 v220, v[40:43]
	ds_write_b128 v220, v[46:49] offset:1024
	ds_write_b128 v220, v[50:53] offset:2048
	ds_write_b128 v220, v[54:57] offset:3072
	ds_write_b128 v220, v[58:61] offset:4096
	ds_write_b128 v220, v[64:67] offset:5120
	ds_write_b128 v220, v[68:71] offset:6144
	ds_write_b128 v220, v[78:81] offset:7168
	ds_write_b128 v220, v[82:85] offset:8192
	ds_write_b128 v220, v[86:89] offset:9216
	ds_write_b128 v220, v[90:93] offset:10240
	ds_write_b128 v220, v[94:97] offset:11264
	ds_write_b128 v220, v[98:101] offset:12288
	ds_write_b128 v220, v[102:105] offset:13312
	ds_write_b128 v220, v[106:109] offset:14336
	ds_write_b128 v220, v[110:113] offset:15360
	s_waitcnt lgkmcnt(0)
	s_barrier
	global_load_ushort v78, v[74:75], off
	global_load_ushort v79, v[74:75], off offset:32
	v_or_b32_e32 v70, 1, v72
	v_lshlrev_b64 v[6:7], 11, v[72:73]
	v_ashrrev_i32_e32 v71, 31, v70
	v_lshl_add_u64 v[6:7], s[38:39], 0, v[6:7]
	v_lshlrev_b64 v[8:9], 12, v[70:71]
	v_lshl_add_u64 v[74:75], v[6:7], 0, v[4:5]
	v_lshl_add_u64 v[6:7], s[60:61], 0, v[8:9]
	v_lshl_add_u64 v[76:77], v[6:7], 0, v[4:5]
	ds_read_b128 v[6:9], v177
	ds_read_b128 v[10:13], v177 offset:1024
	ds_read_b128 v[14:17], v177 offset:16384
	ds_read_b128 v[18:21], v177 offset:17408
	ds_read_b128 v[22:25], v177 offset:32768
	ds_read_b128 v[26:29], v177 offset:33792
	ds_read_b128 v[30:33], v177 offset:49152
	ds_read_b128 v[34:37], v177 offset:50176
	ds_read_b128 v[38:41], v212
	ds_read_b128 v[42:45], v213
	ds_read_b128 v[46:49], v214
	ds_read_b128 v[50:53], v215
	ds_read_b128 v[54:57], v216
	ds_read_b128 v[58:61], v217
	ds_read_b128 v[62:65], v218
	ds_read_b128 v[66:69], v219
	s_waitcnt lgkmcnt(14)
	v_pk_add_f32 v[6:7], v[6:7], 0 op_sel_hi:[1,0]
	v_pk_add_f32 v[10:11], v[10:11], 0 op_sel_hi:[1,0]
	s_waitcnt lgkmcnt(13)
	v_pk_add_f32 v[6:7], v[6:7], v[14:15]
	s_waitcnt lgkmcnt(12)
	v_pk_add_f32 v[10:11], v[10:11], v[18:19]
	s_waitcnt lgkmcnt(11)
	v_pk_add_f32 v[6:7], v[6:7], v[22:23]
	s_waitcnt lgkmcnt(10)
	v_pk_add_f32 v[10:11], v[10:11], v[26:27]
	s_waitcnt lgkmcnt(9)
	v_pk_add_f32 v[6:7], v[6:7], v[30:31]
	s_waitcnt lgkmcnt(8)
	v_pk_add_f32 v[10:11], v[10:11], v[34:35]
	s_waitcnt lgkmcnt(7)
	v_pk_add_f32 v[6:7], v[6:7], v[38:39]
	s_waitcnt lgkmcnt(6)
	v_pk_add_f32 v[10:11], v[10:11], v[42:43]
	s_waitcnt lgkmcnt(5)
	v_pk_add_f32 v[6:7], v[6:7], v[46:47]
	s_waitcnt lgkmcnt(4)
	v_pk_add_f32 v[10:11], v[10:11], v[50:51]
	s_waitcnt lgkmcnt(3)
	v_pk_add_f32 v[6:7], v[6:7], v[54:55]
	s_waitcnt lgkmcnt(2)
	v_pk_add_f32 v[10:11], v[10:11], v[58:59]
	s_waitcnt lgkmcnt(1)
	v_pk_add_f32 v[6:7], v[6:7], v[62:63]
	s_waitcnt lgkmcnt(0)
	v_pk_add_f32 v[10:11], v[10:11], v[66:67]
	v_lshlrev_b64 v[18:19], 11, v[70:71]
	v_lshl_add_u64 v[18:19], s[38:39], 0, v[18:19]
	v_lshl_add_u64 v[18:19], v[18:19], 0, v[4:5]
	v_pk_add_f32 v[8:9], v[8:9], 0 op_sel_hi:[1,0]
	v_pk_add_f32 v[12:13], v[12:13], 0 op_sel_hi:[1,0]
	v_pk_add_f32 v[8:9], v[8:9], v[16:17]
	v_pk_add_f32 v[12:13], v[12:13], v[20:21]
	v_pk_add_f32 v[8:9], v[8:9], v[24:25]
	v_pk_add_f32 v[12:13], v[12:13], v[28:29]
	v_pk_add_f32 v[8:9], v[8:9], v[32:33]
	v_pk_add_f32 v[12:13], v[12:13], v[36:37]
	v_pk_add_f32 v[8:9], v[8:9], v[40:41]
	v_pk_add_f32 v[12:13], v[12:13], v[44:45]
	v_pk_add_f32 v[8:9], v[8:9], v[48:49]
	v_pk_add_f32 v[12:13], v[12:13], v[52:53]
	v_pk_add_f32 v[8:9], v[8:9], v[56:57]
	v_pk_add_f32 v[12:13], v[12:13], v[60:61]
	v_pk_add_f32 v[8:9], v[8:9], v[64:65]
	v_pk_add_f32 v[12:13], v[12:13], v[68:69]
	s_waitcnt vmcnt(1)
	v_lshlrev_b32_e32 v14, 16, v78
	s_waitcnt vmcnt(0)
	v_lshlrev_b32_e32 v15, 16, v79
	v_mul_f32_e32 v14, 0xbfb8aa3b, v14
	v_mul_f32_e32 v15, 0xbfb8aa3b, v15
	v_exp_f32_e32 v14, v14
	v_exp_f32_e32 v15, v15
	v_add_f32_e32 v14, 1.0, v14
	v_add_f32_e32 v15, 1.0, v15
	v_rcp_f32_e32 v14, v14
	v_rcp_f32_e32 v15, v15
	v_mul_f32_e32 v6, v6, v14
	v_mul_f32_e32 v10, v10, v15
	v_bfe_u32 v14, v6, 16, 1
	v_bfe_u32 v15, v10, 16, 1
	v_add3_u32 v6, v6, v14, s24
	v_add3_u32 v10, v10, v15, s24
	global_store_short_d16_hi v[74:75], v6, off
	global_store_short_d16_hi v[74:75], v10, off offset:32
	global_load_ushort v6, v[76:77], off
	s_nop 0
	global_load_ushort v10, v[76:77], off offset:32
	v_or_b32_e32 v14, 2, v72
	v_ashrrev_i32_e32 v15, 31, v14
	v_lshlrev_b64 v[22:23], 12, v[14:15]
	v_lshl_add_u64 v[22:23], s[60:61], 0, v[22:23]
	v_lshl_add_u64 v[22:23], v[22:23], 0, v[4:5]
	s_waitcnt vmcnt(1)
	v_lshlrev_b32_e32 v6, 16, v6
	s_waitcnt vmcnt(0)
	v_lshlrev_b32_e32 v10, 16, v10
	v_mul_f32_e32 v6, 0xbfb8aa3b, v6
	v_mul_f32_e32 v10, 0xbfb8aa3b, v10
	v_exp_f32_e32 v6, v6
	v_exp_f32_e32 v10, v10
	v_add_f32_e32 v6, 1.0, v6
	v_add_f32_e32 v10, 1.0, v10
	v_rcp_f32_e32 v6, v6
	v_rcp_f32_e32 v10, v10
	v_mul_f32_e32 v6, v7, v6
	v_mul_f32_e32 v7, v11, v10
	v_bfe_u32 v10, v6, 16, 1
	v_bfe_u32 v11, v7, 16, 1
	v_add3_u32 v6, v6, v10, s24
	v_add3_u32 v7, v7, v11, s24
	global_store_short_d16_hi v[18:19], v6, off
	global_store_short_d16_hi v[18:19], v7, off offset:32
	global_load_ushort v18, v[22:23], off
	s_nop 0
	global_load_ushort v19, v[22:23], off offset:32
	v_or_b32_e32 v6, 3, v72
	v_ashrrev_i32_e32 v7, 31, v6
	v_lshlrev_b64 v[10:11], 11, v[14:15]
	v_lshlrev_b64 v[14:15], 12, v[6:7]
	v_lshl_add_u64 v[10:11], s[38:39], 0, v[10:11]
	v_lshl_add_u64 v[14:15], s[60:61], 0, v[14:15]
	v_lshl_add_u64 v[10:11], v[10:11], 0, v[4:5]
	v_lshl_add_u64 v[14:15], v[14:15], 0, v[4:5]
	v_lshlrev_b64 v[6:7], 11, v[6:7]
	v_lshl_add_u64 v[6:7], s[38:39], 0, v[6:7]
	v_lshl_add_u64 v[4:5], v[6:7], 0, v[4:5]
	s_waitcnt vmcnt(1)
	v_lshlrev_b32_e32 v16, 16, v18
	s_waitcnt vmcnt(0)
	v_lshlrev_b32_e32 v17, 16, v19
	v_mul_f32_e32 v16, 0xbfb8aa3b, v16
	v_mul_f32_e32 v17, 0xbfb8aa3b, v17
	v_exp_f32_e32 v16, v16
	v_exp_f32_e32 v17, v17
	v_add_f32_e32 v16, 1.0, v16
	v_add_f32_e32 v17, 1.0, v17
	v_rcp_f32_e32 v16, v16
	v_rcp_f32_e32 v17, v17
	v_mul_f32_e32 v8, v8, v16
	v_mul_f32_e32 v12, v12, v17
	v_bfe_u32 v16, v8, 16, 1
	v_bfe_u32 v17, v12, 16, 1
	v_add3_u32 v8, v8, v16, s24
	v_add3_u32 v12, v12, v17, s24
	global_store_short_d16_hi v[10:11], v8, off
	global_store_short_d16_hi v[10:11], v12, off offset:32
	global_load_ushort v8, v[14:15], off
	s_nop 0
	global_load_ushort v10, v[14:15], off offset:32
	s_waitcnt vmcnt(1)
	v_lshlrev_b32_e32 v6, 16, v8
	s_waitcnt vmcnt(0)
	v_lshlrev_b32_e32 v7, 16, v10
	v_mul_f32_e32 v6, 0xbfb8aa3b, v6
	v_mul_f32_e32 v7, 0xbfb8aa3b, v7
	v_exp_f32_e32 v6, v6
	v_exp_f32_e32 v7, v7
	v_add_f32_e32 v6, 1.0, v6
	v_add_f32_e32 v7, 1.0, v7
	v_rcp_f32_e32 v6, v6
	v_rcp_f32_e32 v7, v7
	v_mul_f32_e32 v6, v9, v6
	v_mul_f32_e32 v7, v13, v7
	v_bfe_u32 v8, v6, 16, 1
	v_bfe_u32 v9, v7, 16, 1
	v_add3_u32 v6, v6, v8, s24
	v_add3_u32 v7, v7, v9, s24
	global_store_short_d16_hi v[4:5], v6, off
	global_store_short_d16_hi v[4:5], v7, off offset:32
	s_cbranch_scc1 .LBB0_1014

.LBB0_1033:
	s_mov_b32 s40, 0x4000
	s_mov_b32 s41, 0
	s_mov_b32 s42, 0x8000
	s_mov_b32 s43, 0
	s_mov_b32 s44, 0xc000
	s_mov_b32 s45, 0
	s_ashr_i32 s24, s23, 4
	s_add_i32 s24, s24, s33
	s_ashr_i32 s25, s24, 31
	s_lshr_b32 s25, s25, 29
	s_add_i32 s25, s24, s25
	s_ashr_i32 s26, s25, 3
	s_and_b32 s25, s25, -8
	s_sub_i32 s24, s24, s25
	s_cmp_lt_i32 s24, 0
	s_cselect_b32 s25, 35, 34
	s_mul_i32 s24, s24, s25
	s_add_i32 s24, s24, s26
	s_ashr_i32 s25, s24, 31
	s_lshr_b32 s25, s25, 27
	s_add_i32 s25, s24, s25
	s_ashr_i32 s26, s25, 5
	s_andn2_b32 s25, s25, 31
	s_lshl_b32 s26, s26, 3
	s_sub_i32 s25, s24, s25
	s_sub_i32 s24, 0x44, s26
	s_min_i32 s24, s24, 8
	s_abs_i32 s29, s24
	v_cvt_f32_u32_e32 v0, s29
	s_sub_i32 s30, 0, s29
	s_abs_i32 s27, s25
	s_xor_b32 s28, s25, s24
	v_rcp_iflag_f32_e32 v0, v0
	s_ashr_i32 s28, s28, 31
	v_mul_f32_e32 v0, 0x4f7ffffe, v0
	v_cvt_u32_f32_e32 v0, v0
	s_nop 0
	v_readfirstlane_b32 s31, v0
	s_mul_i32 s30, s30, s31
	s_mul_hi_u32 s30, s31, s30
	s_add_i32 s31, s31, s30
	s_mul_hi_u32 s30, s27, s31
	s_mul_i32 s31, s30, s29
	s_sub_i32 s27, s27, s31
	s_add_i32 s34, s30, 1
	s_sub_i32 s31, s27, s29
	s_cmp_ge_u32 s27, s29
	s_cselect_b32 s30, s34, s30
	s_cselect_b32 s27, s31, s27
	s_add_i32 s31, s30, 1
	s_cmp_ge_u32 s27, s29
	s_cselect_b32 s27, s31, s30
	s_xor_b32 s27, s27, s28
	s_sub_i32 s27, s27, s28
	s_mul_i32 s28, s27, s24
	s_waitcnt vmcnt(0) lgkmcnt(0)
	s_lshl_b32 s24, s27, 8
	s_and_b32 s32, s2, 0x30
	s_lshl_b32 s32, s32, 2
	s_or_b32 s24, s24, s32
	v_or_b32_e32 v0, s24, v179
	v_ashrrev_i32_e32 v1, 31, v0
	v_lshlrev_b64 v[0:1], 10, v[0:1]
	v_lshl_add_u64 v[238:239], v[94:95], 0, v[0:1]
	s_sub_i32 s25, s25, s28
	s_add_i32 s26, s26, s25
	s_and_b32 s29, s2, 0xc0
	s_lshl_b32 s25, s26, 8
	s_or_b32 s25, s25, s29
	v_or_b32_e32 v2, s25, v179
	v_ashrrev_i32_e32 v3, 31, v2
	s_add_i32 s23, s23, s94
	s_add_i32 s2, s2, s72
	v_lshlrev_b64 v[0:1], 10, v[2:3]
	v_lshl_add_u64 v[46:47], v[92:93], 0, v[0:1]
	s_cmp_lt_i32 s23, s36
	v_lshl_add_u64 v[174:175], v[46:47], 0, s[40:41]
	v_lshl_add_u64 v[240:241], v[238:239], 0, s[40:41]
	v_lshl_add_u64 v[234:235], v[46:47], 0, s[42:43]
	v_lshl_add_u64 v[242:243], v[238:239], 0, s[42:43]
	v_lshl_add_u64 v[236:237], v[46:47], 0, s[44:45]
	v_lshl_add_u64 v[244:245], v[238:239], 0, s[44:45]
	global_load_dwordx4 v[146:149], v[46:47], off
	global_load_dwordx4 v[150:153], v[46:47], off offset:64
	global_load_dwordx4 v[154:157], v[174:175], off
	global_load_dwordx4 v[158:161], v[174:175], off offset:64
	global_load_dwordx4 v[162:165], v[234:235], off
	global_load_dwordx4 v[166:169], v[234:235], off offset:64
	global_load_dwordx4 v[170:173], v[236:237], off
	global_load_dwordx4 v[184:187], v[236:237], off offset:64
	global_load_dwordx4 v[188:191], v[238:239], off
	global_load_dwordx4 v[192:195], v[238:239], off offset:64
	global_load_dwordx4 v[196:199], v[240:241], off
	global_load_dwordx4 v[200:203], v[240:241], off offset:64
	global_load_dwordx4 v[204:207], v[242:243], off
	global_load_dwordx4 v[222:225], v[242:243], off offset:64
	global_load_dwordx4 v[226:229], v[244:245], off
	global_load_dwordx4 v[230:233], v[244:245], off offset:64
	s_waitcnt vmcnt(0)
	v_mfma_f32_16x16x32_bf16 v[40:43], v[146:149], v[188:191], 0
	v_mfma_f32_16x16x32_bf16 v[52:55], v[146:149], v[196:199], 0
	v_mfma_f32_16x16x32_bf16 v[60:63], v[146:149], v[204:207], 0
	v_mfma_f32_16x16x32_bf16 v[68:71], v[146:149], v[226:229], 0
	v_mfma_f32_16x16x32_bf16 v[76:79], v[154:157], v[188:191], 0
	v_mfma_f32_16x16x32_bf16 v[84:87], v[154:157], v[196:199], 0
	v_mfma_f32_16x16x32_bf16 v[98:101], v[154:157], v[204:207], 0
	v_mfma_f32_16x16x32_bf16 v[102:105], v[154:157], v[226:229], 0
	v_mfma_f32_16x16x32_bf16 v[114:117], v[162:165], v[188:191], 0
	v_mfma_f32_16x16x32_bf16 v[118:121], v[162:165], v[196:199], 0
	v_mfma_f32_16x16x32_bf16 v[122:125], v[162:165], v[204:207], 0
	v_mfma_f32_16x16x32_bf16 v[126:129], v[162:165], v[226:229], 0
	v_mfma_f32_16x16x32_bf16 v[130:133], v[170:173], v[188:191], 0
	v_mfma_f32_16x16x32_bf16 v[134:137], v[170:173], v[196:199], 0
	v_mfma_f32_16x16x32_bf16 v[138:141], v[170:173], v[204:207], 0
	v_mfma_f32_16x16x32_bf16 v[142:145], v[170:173], v[226:229], 0
	v_mfma_f32_16x16x32_bf16 v[40:43], v[150:153], v[192:195], v[40:43]
	v_mfma_f32_16x16x32_bf16 v[52:55], v[150:153], v[200:203], v[52:55]
	v_mfma_f32_16x16x32_bf16 v[60:63], v[150:153], v[222:225], v[60:63]
	v_mfma_f32_16x16x32_bf16 v[68:71], v[150:153], v[230:233], v[68:71]
	v_mfma_f32_16x16x32_bf16 v[76:79], v[158:161], v[192:195], v[76:79]
	v_mfma_f32_16x16x32_bf16 v[84:87], v[158:161], v[200:203], v[84:87]
	v_mfma_f32_16x16x32_bf16 v[98:101], v[158:161], v[222:225], v[98:101]
	v_mfma_f32_16x16x32_bf16 v[102:105], v[158:161], v[230:233], v[102:105]
	v_mfma_f32_16x16x32_bf16 v[114:117], v[166:169], v[192:195], v[114:117]
	v_mfma_f32_16x16x32_bf16 v[118:121], v[166:169], v[200:203], v[118:121]
	v_mfma_f32_16x16x32_bf16 v[122:125], v[166:169], v[222:225], v[122:125]
	v_mfma_f32_16x16x32_bf16 v[126:129], v[166:169], v[230:233], v[126:129]
	v_mfma_f32_16x16x32_bf16 v[130:133], v[184:187], v[192:195], v[130:133]
	v_mfma_f32_16x16x32_bf16 v[134:137], v[184:187], v[200:203], v[134:137]
	v_mfma_f32_16x16x32_bf16 v[138:141], v[184:187], v[222:225], v[138:141]
	v_mfma_f32_16x16x32_bf16 v[142:145], v[184:187], v[230:233], v[142:145]
	s_barrier
	v_and_b32_e32 v8, 0x2f, v211
	v_add_u32_e32 v96, s24, v8
	v_ashrrev_i32_e32 v97, 31, v96
	v_lshlrev_b64 v[96:97], 1, v[96:97]
	v_lshrrev_b32_e32 v8, 2, v211
	v_and_b32_e32 v8, 0x30, v8
	v_or3_b32 v106, v8, v210, s25
	v_ashrrev_i32_e32 v107, 31, v106
	v_or_b32_e32 v108, 1, v106
	v_or_b32_e32 v110, 2, v106
	v_ashrrev_i32_e32 v109, 31, v108
	v_ashrrev_i32_e32 v111, 31, v110
	v_or_b32_e32 v112, 3, v106
	v_ashrrev_i32_e32 v113, 31, v112
	v_lshlrev_b64 v[88:89], 12, v[106:107]
	v_lshlrev_b64 v[90:91], 11, v[106:107]
	v_lshl_add_u64 v[80:81], s[0:1], 0, v[88:89]
	v_lshlrev_b64 v[82:83], 11, v[110:111]
	v_lshlrev_b64 v[74:75], 11, v[108:109]
	v_lshl_add_u64 v[72:73], s[38:39], 0, v[90:91]
	v_lshlrev_b64 v[64:65], 11, v[112:113]
	v_lshl_add_u64 v[66:67], v[72:73], 0, v[96:97]
	v_lshl_add_u64 v[56:57], v[80:81], 0, v[96:97]
	v_lshl_add_u64 v[58:59], s[38:39], 0, v[64:65]
	v_lshl_add_u64 v[48:49], s[38:39], 0, v[74:75]
	v_lshl_add_u64 v[50:51], s[38:39], 0, v[82:83]
	v_lshl_add_u64 v[64:65], v[48:49], 0, v[96:97]
	v_lshl_add_u64 v[72:73], v[50:51], 0, v[96:97]
	v_lshl_add_u64 v[74:75], v[58:59], 0, v[96:97]
	ds_write_b128 v220, v[40:43]
	ds_write_b128 v220, v[52:55] offset:1024
	ds_write_b128 v220, v[60:63] offset:2048
	ds_write_b128 v220, v[68:71] offset:3072
	ds_write_b128 v220, v[76:79] offset:4096
	ds_write_b128 v220, v[84:87] offset:5120
	ds_write_b128 v220, v[98:101] offset:6144
	ds_write_b128 v220, v[102:105] offset:7168
	ds_write_b128 v220, v[114:117] offset:8192
	ds_write_b128 v220, v[118:121] offset:9216
	ds_write_b128 v220, v[122:125] offset:10240
	ds_write_b128 v220, v[126:129] offset:11264
	ds_write_b128 v220, v[130:133] offset:12288
	ds_write_b128 v220, v[134:137] offset:13312
	ds_write_b128 v220, v[138:141] offset:14336
	ds_write_b128 v220, v[142:145] offset:15360
	s_waitcnt lgkmcnt(0)
	s_barrier
	global_load_ushort v70, v[56:57], off
	global_load_ushort v71, v[66:67], off
	global_load_ushort v76, v[66:67], off offset:32
	global_load_ushort v77, v[64:65], off
	global_load_ushort v78, v[72:73], off
	global_load_ushort v79, v[74:75], off offset:32
	global_load_ushort v80, v[56:57], off offset:32
	v_lshlrev_b64 v[0:1], 12, v[108:109]
	v_lshl_add_u64 v[0:1], s[0:1], 0, v[0:1]
	v_lshl_add_u64 v[68:69], v[0:1], 0, v[96:97]
	ds_read_b128 v[0:3], v177
	ds_read_b128 v[4:7], v177 offset:1024
	ds_read_b128 v[8:11], v177 offset:16384
	ds_read_b128 v[12:15], v177 offset:17408
	ds_read_b128 v[16:19], v177 offset:32768
	ds_read_b128 v[20:23], v177 offset:33792
	ds_read_b128 v[24:27], v177 offset:49152
	ds_read_b128 v[28:31], v177 offset:50176
	ds_read_b128 v[32:35], v212
	ds_read_b128 v[36:39], v213
	ds_read_b128 v[40:43], v214
	ds_read_b128 v[44:47], v215
	ds_read_b128 v[48:51], v216
	ds_read_b128 v[52:55], v217
	ds_read_b128 v[56:59], v218
	ds_read_b128 v[60:63], v219
	s_waitcnt lgkmcnt(14)
	v_pk_add_f32 v[0:1], v[0:1], 0 op_sel_hi:[1,0]
	v_pk_add_f32 v[4:5], v[4:5], 0 op_sel_hi:[1,0]
	s_waitcnt lgkmcnt(13)
	v_pk_add_f32 v[0:1], v[0:1], v[8:9]
	s_waitcnt lgkmcnt(12)
	v_pk_add_f32 v[4:5], v[4:5], v[12:13]
	s_waitcnt lgkmcnt(11)
	v_pk_add_f32 v[0:1], v[0:1], v[16:17]
	s_waitcnt lgkmcnt(10)
	v_pk_add_f32 v[4:5], v[4:5], v[20:21]
	s_waitcnt lgkmcnt(9)
	v_pk_add_f32 v[0:1], v[0:1], v[24:25]
	s_waitcnt lgkmcnt(8)
	v_pk_add_f32 v[4:5], v[4:5], v[28:29]
	s_waitcnt lgkmcnt(7)
	v_pk_add_f32 v[0:1], v[0:1], v[32:33]
	s_waitcnt lgkmcnt(6)
	v_pk_add_f32 v[4:5], v[4:5], v[36:37]
	s_waitcnt lgkmcnt(5)
	v_pk_add_f32 v[0:1], v[0:1], v[40:41]
	s_waitcnt lgkmcnt(4)
	v_pk_add_f32 v[4:5], v[4:5], v[44:45]
	s_waitcnt lgkmcnt(3)
	v_pk_add_f32 v[0:1], v[0:1], v[48:49]
	s_waitcnt lgkmcnt(2)
	v_pk_add_f32 v[4:5], v[4:5], v[52:53]
	s_waitcnt lgkmcnt(1)
	v_pk_add_f32 v[0:1], v[0:1], v[56:57]
	s_waitcnt lgkmcnt(0)
	v_pk_add_f32 v[4:5], v[4:5], v[60:61]
	v_pk_add_f32 v[2:3], v[2:3], 0 op_sel_hi:[1,0]
	s_waitcnt vmcnt(6)
	v_lshlrev_b32_e32 v8, 16, v70
	v_mul_f32_e32 v8, 0xbfb8aa3b, v8
	v_exp_f32_e32 v8, v8
	s_waitcnt vmcnt(5)
	v_lshlrev_b32_e32 v9, 16, v71
	s_waitcnt vmcnt(4)
	v_lshlrev_b32_e32 v13, 16, v76
	v_pk_add_f32 v[2:3], v[2:3], v[10:11]
	s_waitcnt vmcnt(0)
	v_lshlrev_b32_e32 v12, 16, v80
	v_mul_f32_e32 v12, 0xbfb8aa3b, v12
	v_exp_f32_e32 v12, v12
	v_add_f32_e32 v8, 1.0, v8
	v_rcp_f32_e32 v8, v8
	v_pk_add_f32 v[2:3], v[2:3], v[18:19]
	v_add_f32_e32 v12, 1.0, v12
	v_rcp_f32_e32 v12, v12
	v_fmac_f32_e32 v9, v0, v8
	v_bfe_u32 v0, v9, 16, 1
	v_add3_u32 v0, v9, v0, s22
	v_fmac_f32_e32 v13, v4, v12
	v_bfe_u32 v4, v13, 16, 1
	v_add3_u32 v4, v13, v4, s22
	global_store_short_d16_hi v[66:67], v0, off
	global_store_short_d16_hi v[66:67], v4, off offset:32
	global_load_ushort v0, v[68:69], off
	s_nop 0
	global_load_ushort v4, v[68:69], off offset:32
	global_load_ushort v12, v[64:65], off offset:32
	v_lshlrev_b32_e32 v13, 16, v77
	v_lshlrev_b64 v[8:9], 12, v[110:111]
	v_lshl_add_u64 v[8:9], s[0:1], 0, v[8:9]
	v_lshl_add_u64 v[8:9], v[8:9], 0, v[96:97]
	global_load_ushort v16, v[72:73], off offset:32
	v_pk_add_f32 v[2:3], v[2:3], v[26:27]
	s_waitcnt vmcnt(3)
	v_lshlrev_b32_e32 v0, 16, v0
	s_waitcnt vmcnt(2)
	v_lshlrev_b32_e32 v4, 16, v4
	v_mul_f32_e32 v0, 0xbfb8aa3b, v0
	v_mul_f32_e32 v4, 0xbfb8aa3b, v4
	v_exp_f32_e32 v0, v0
	v_exp_f32_e32 v4, v4
	s_waitcnt vmcnt(1)
	v_lshlrev_b32_e32 v12, 16, v12
	v_pk_add_f32 v[2:3], v[2:3], v[34:35]
	v_add_f32_e32 v0, 1.0, v0
	v_add_f32_e32 v4, 1.0, v4
	v_rcp_f32_e32 v0, v0
	v_rcp_f32_e32 v4, v4
	v_pk_add_f32 v[2:3], v[2:3], v[42:43]
	v_fmac_f32_e32 v13, v1, v0
	v_fmac_f32_e32 v12, v5, v4
	v_bfe_u32 v0, v13, 16, 1
	v_bfe_u32 v1, v12, 16, 1
	v_add3_u32 v0, v13, v0, s22
	v_add3_u32 v1, v12, v1, s22
	global_store_short_d16_hi v[64:65], v0, off
	global_store_short_d16_hi v[64:65], v1, off offset:32
	global_load_ushort v12, v[8:9], off
	s_nop 0
	global_load_ushort v8, v[8:9], off offset:32
	v_pk_add_f32 v[4:5], v[6:7], 0 op_sel_hi:[1,0]
	v_pk_add_f32 v[2:3], v[2:3], v[50:51]
	v_pk_add_f32 v[4:5], v[4:5], v[14:15]
	v_pk_add_f32 v[2:3], v[2:3], v[58:59]
	v_pk_add_f32 v[4:5], v[4:5], v[22:23]
	v_lshlrev_b32_e32 v6, 16, v78
	v_pk_add_f32 v[4:5], v[4:5], v[30:31]
	s_waitcnt vmcnt(4)
	v_lshlrev_b32_e32 v7, 16, v16
	v_pk_add_f32 v[4:5], v[4:5], v[38:39]
	v_lshlrev_b64 v[0:1], 12, v[112:113]
	v_pk_add_f32 v[4:5], v[4:5], v[46:47]
	v_lshl_add_u64 v[0:1], s[0:1], 0, v[0:1]
	v_pk_add_f32 v[4:5], v[4:5], v[54:55]
	v_lshl_add_u64 v[0:1], v[0:1], 0, v[96:97]
	v_pk_add_f32 v[4:5], v[4:5], v[62:63]
	global_load_ushort v9, v[74:75], off
	s_waitcnt vmcnt(2)
	v_lshlrev_b32_e32 v10, 16, v12
	s_waitcnt vmcnt(1)
	v_lshlrev_b32_e32 v8, 16, v8
	v_mul_f32_e32 v10, 0xbfb8aa3b, v10
	v_mul_f32_e32 v8, 0xbfb8aa3b, v8
	v_exp_f32_e32 v10, v10
	v_exp_f32_e32 v8, v8
	v_add_f32_e32 v10, 1.0, v10
	v_add_f32_e32 v8, 1.0, v8
	v_rcp_f32_e32 v10, v10
	v_rcp_f32_e32 v8, v8
	v_fmac_f32_e32 v6, v2, v10
	v_fmac_f32_e32 v7, v4, v8
	v_bfe_u32 v2, v6, 16, 1
	v_bfe_u32 v4, v7, 16, 1
	v_add3_u32 v2, v6, v2, s22
	v_add3_u32 v4, v7, v4, s22
	global_store_short_d16_hi v[72:73], v2, off
	global_store_short_d16_hi v[72:73], v4, off offset:32
	global_load_ushort v2, v[0:1], off
	s_nop 0
	global_load_ushort v0, v[0:1], off offset:32
	s_waitcnt vmcnt(4)
	v_lshlrev_b32_e32 v4, 16, v9
	v_lshlrev_b32_e32 v1, 16, v79
	s_waitcnt vmcnt(1)
	v_lshlrev_b32_e32 v2, 16, v2
	s_waitcnt vmcnt(0)
	v_lshlrev_b32_e32 v0, 16, v0
	v_mul_f32_e32 v2, 0xbfb8aa3b, v2
	v_mul_f32_e32 v0, 0xbfb8aa3b, v0
	v_exp_f32_e32 v2, v2
	v_exp_f32_e32 v0, v0
	v_add_f32_e32 v2, 1.0, v2
	v_add_f32_e32 v0, 1.0, v0
	v_rcp_f32_e32 v2, v2
	v_rcp_f32_e32 v0, v0
	v_fmac_f32_e32 v4, v3, v2
	v_fmac_f32_e32 v1, v5, v0
	v_bfe_u32 v0, v4, 16, 1
	v_bfe_u32 v2, v1, 16, 1
	v_add3_u32 v0, v4, v0, s22
	v_add3_u32 v1, v1, v2, s22
	global_store_short_d16_hi v[74:75], v0, off
	global_store_short_d16_hi v[74:75], v1, off offset:32
	s_cbranch_scc1 .LBB0_1033
